# v36 + L1-only invalidate (buffer_inv sc0) in the three panel/group barriers when the group is verified same-XCD (shared L2), full sc1 otherwise
# speedup vs baseline: 1.0201x; 1.0050x over previous
; __device__ __forceinline__ unsigned xb_ld(unsigned* p)              { return __hip_atomic_load(p, __ATOMIC_RELAXED, __HIP_MEMORY_SCOPE_AGENT); }
; __device__ __forceinline__ unsigned xb_add(unsigned* p, unsigned v) { return __hip_atomic_fetch_add(p, v, __ATOMIC_RELAXED, __HIP_MEMORY_SCOPE_AGENT); }
; #define XB_SPIN(cond, bar) do { unsigned _sp = 0; while (cond) { __builtin_amdgcn_s_sleep(1); \
;     if ((++_sp & 255u) == 0u) { if (xb_ld(&(bar)[XB_TMO])) break; if (_sp > XB_SPIN_CAP) { atomicAdd(&(bar)[XB_TMO], 1u); break; } } } } while (0)
; __device__ __forceinline__ void xcd_barrier(const XcdBarrier& b) {
;     asm volatile("s_waitcnt vmcnt(0)" ::: "memory");
;     __syncthreads();
;     if (threadIdx.x == 0) {
;         unsigned* bar = b.bar;
;         __builtin_amdgcn_s_waitcnt(0);
;         unsigned nloc = b.st[0], nx = b.st[1];
;         if (nloc == 0u) { xcd_barrier_complete(bar, b.x, nloc, nx); b.st[0] = nloc; b.st[1] = nx; }
;         const unsigned old = xb_add(&bar[XB_XSUB(b.x)], 1u);
;         const unsigned gen = old / nloc;
;         if (old + 1u == (gen + 1u) * nloc) {
;             __builtin_amdgcn_fence(__ATOMIC_RELEASE, "agent");
;             asm volatile("s_waitcnt vmcnt(0)" ::: "memory");
;             const unsigned og = xb_add(&bar[XB_TOP], 1u);
;             const unsigned tg = og / nx;
;             if (og + 1u == (tg + 1u) * nx) xb_add(&bar[XB_TOPGEN], 1u);
;             else XB_SPIN(xb_ld(&bar[XB_TOPGEN]) == tg, bar);
;             __builtin_amdgcn_fence(__ATOMIC_ACQUIRE, "agent");
;             xb_add(&bar[XB_XGEN(b.x)], 1u);
;             asm volatile("s_waitcnt vmcnt(0)" ::: "memory");
;         } else {
;             XB_SPIN(xb_ld(&bar[XB_XGEN(b.x)]) == gen, bar);
;             __builtin_amdgcn_fence(__ATOMIC_ACQUIRE, "agent");
;             asm volatile("s_waitcnt vmcnt(0)" ::: "memory");
;         }
;     }
;     __syncthreads();
; }
.Lgd_done:
	s_cmp_eq_u32 s98, 1
	s_cbranch_scc1 .Lgd_l1
	buffer_inv sc1
	s_branch .Lgd_ij
.Lgd_l1:
	buffer_inv sc0
.Lgd_ij:
	s_waitcnt vmcnt(0)
	s_branch .LBB0_775
